# XCD grid barrier: non-last workgroups poll the top generation word directly instead of waiting for their XCD-last workgroup to republish it (one fewer memory hop per barrier); republish atomic dropped
# speedup vs baseline: 1.0151x; 1.0078x over previous
; DI unsigned xb_ld(unsigned* p)              { return __hip_atomic_load(p, __ATOMIC_RELAXED, __HIP_MEMORY_SCOPE_AGENT); }
; DI unsigned xb_add(unsigned* p, unsigned v) { return __hip_atomic_fetch_add(p, v, __ATOMIC_RELAXED, __HIP_MEMORY_SCOPE_AGENT); }
; #define XB_SPIN(cond, bar) do { unsigned _sp = 0; while (cond) { __builtin_amdgcn_s_sleep(1); \
;     if ((++_sp & 255u) == 0u) { if (xb_ld(&(bar)[XB_TMO])) break; if (_sp > XB_SPIN_CAP) { atomicAdd(&(bar)[XB_TMO], 1u); break; } } } } while (0)
; DI void xcd_barrier(const XcdBarrier& b) {
;     ...
;         unsigned nloc = b.st[0], nx = b.st[1];
;         if (nloc == 0u) { xcd_barrier_complete(bar, b.x, nloc, nx); b.st[0] = nloc; b.st[1] = nx; }
;         const unsigned old = xb_add(&bar[XB_XSUB(b.x)], 1u);
;         const unsigned gen = old / nloc;
;         if (old + 1u == (gen + 1u) * nloc) {
;             __builtin_amdgcn_fence(__ATOMIC_RELEASE, "agent");
;             asm volatile("s_waitcnt vmcnt(0)" ::: "memory");
;             const unsigned og = xb_add(&bar[XB_TOP], 1u);
;             const unsigned tg = og / nx;
;             if (og + 1u == (tg + 1u) * nx) xb_add(&bar[XB_TOPGEN], 1u);
;             else XB_SPIN(xb_ld(&bar[XB_TOPGEN]) == tg, bar);
;             __builtin_amdgcn_fence(__ATOMIC_ACQUIRE, "agent");
;             xb_add(&bar[XB_XGEN(b.x)], 1u);
;             asm volatile("s_waitcnt vmcnt(0)" ::: "memory");
;         } else {
;             XB_SPIN(xb_ld(&bar[XB_XGEN(b.x)]) == gen, bar);
.LBB0_174:
	s_or_b64 exec, exec, s[4:5]
	v_cvt_f32_u32_e32 v6, v3
	s_waitcnt vmcnt(0)
	v_readfirstlane_b32 s0, v5
	v_sub_u32_e32 v5, 0, v3
	v_rcp_iflag_f32_e32 v6, v6
	v_add_u32_e32 v7, s0, v1
	v_mul_f32_e32 v6, 0x4f7ffffe, v6
	v_cvt_u32_f32_e32 v6, v6
	v_mul_lo_u32 v1, v5, v6
	v_mul_hi_u32 v1, v6, v1
	v_add_u32_e32 v1, v6, v1
	v_mul_hi_u32 v1, v7, v1
	v_mul_lo_u32 v5, v1, v3
	v_sub_u32_e32 v5, v7, v5
	v_add_u32_e32 v6, 1, v1
	v_cmp_ge_u32_e32 vcc, v5, v3
	s_nop 1
	v_cndmask_b32_e32 v1, v1, v6, vcc
	v_sub_u32_e32 v6, v5, v3
	v_cndmask_b32_e32 v5, v5, v6, vcc
	v_add_u32_e32 v6, 1, v1
	v_cmp_ge_u32_e32 vcc, v5, v3
	v_add_u32_e32 v5, 1, v7
	s_nop 0
	v_cndmask_b32_e32 v1, v1, v6, vcc
	v_mul_lo_u32 v6, v3, v1
	v_add_u32_e32 v3, v6, v3
	v_cmp_ne_u32_e32 vcc, v5, v3
	s_and_saveexec_b64 s[0:1], vcc
	s_xor_b64 s[4:5], exec, s[0:1]
	s_cbranch_execz .LBB0_188
	v_readlane_b32 s0, v253, 47
	v_readlane_b32 s1, v253, 48
	s_waitcnt lgkmcnt(0)
	s_nop 3
	global_load_dword v2, v0, s[0:1] sc1
	s_waitcnt vmcnt(0)
	v_cmp_eq_u32_e32 vcc, v2, v1
	s_and_saveexec_b64 s[6:7], vcc
	s_cbranch_execz .LBB0_187
	s_mov_b32 s0, 1
	s_mov_b64 s[8:9], 0
	s_branch .LBB0_178

; DI unsigned xb_add(unsigned* p, unsigned v) { return __hip_atomic_fetch_add(p, v, __ATOMIC_RELAXED, __HIP_MEMORY_SCOPE_AGENT); }
; DI void xcd_barrier(const XcdBarrier& b) {
;     ...
;             __builtin_amdgcn_fence(__ATOMIC_ACQUIRE, "agent");
;             xb_add(&bar[XB_XGEN(b.x)], 1u);
;             asm volatile("s_waitcnt vmcnt(0)" ::: "memory");
.LBB0_205:
	s_or_b64 exec, exec, s[6:7]
	s_mov_b64 s[6:7], exec
	v_mbcnt_lo_u32_b32 v1, s6, 0
	v_mbcnt_hi_u32_b32 v1, s7, v1
	v_cmp_eq_u32_e32 vcc, 0, v1
	s_waitcnt vmcnt(0)
	buffer_inv sc1
	s_and_saveexec_b64 s[8:9], vcc
	s_cbranch_execz .LBB0_207
	s_bcnt1_i32_b64 s0, s[6:7]
	v_mov_b32_e32 v1, s0
	v_readlane_b32 s0, v253, 43
	v_readlane_b32 s1, v253, 44
	s_nop 4
.LBB0_207:
	s_or_b64 exec, exec, s[8:9]
	s_waitcnt vmcnt(0)

; DI unsigned xb_add(unsigned* p, unsigned v) { return __hip_atomic_fetch_add(p, v, __ATOMIC_RELAXED, __HIP_MEMORY_SCOPE_AGENT); }
; DI void xcd_barrier(const XcdBarrier& b) {
;     ...
;             __builtin_amdgcn_fence(__ATOMIC_ACQUIRE, "agent");
;             xb_add(&bar[XB_XGEN(b.x)], 1u);
;             asm volatile("s_waitcnt vmcnt(0)" ::: "memory");
.LBB0_332:
	s_or_b64 exec, exec, s[6:7]
	s_mov_b64 s[6:7], exec
	v_mbcnt_lo_u32_b32 v1, s6, 0
	v_mbcnt_hi_u32_b32 v1, s7, v1
	v_cmp_eq_u32_e32 vcc, 0, v1
	s_waitcnt vmcnt(0)
	buffer_inv sc1
	s_and_saveexec_b64 s[8:9], vcc
	s_cbranch_execz .LBB0_334
	s_bcnt1_i32_b64 s0, s[6:7]
	v_mov_b32_e32 v1, s0
	v_readlane_b32 s0, v253, 43
	v_readlane_b32 s1, v253, 44
	s_nop 4
.LBB0_334:
	s_or_b64 exec, exec, s[8:9]
	s_waitcnt vmcnt(0)

; DI unsigned xb_add(unsigned* p, unsigned v) { return __hip_atomic_fetch_add(p, v, __ATOMIC_RELAXED, __HIP_MEMORY_SCOPE_AGENT); }
; DI void xcd_barrier(const XcdBarrier& b) {
;     ...
;             __builtin_amdgcn_fence(__ATOMIC_ACQUIRE, "agent");
;             xb_add(&bar[XB_XGEN(b.x)], 1u);
;             asm volatile("s_waitcnt vmcnt(0)" ::: "memory");
.LBB0_390:
	s_or_b64 exec, exec, s[4:5]
	s_mov_b64 s[4:5], exec
	v_mbcnt_lo_u32_b32 v1, s4, 0
	v_mbcnt_hi_u32_b32 v1, s5, v1
	v_cmp_eq_u32_e32 vcc, 0, v1
	s_waitcnt vmcnt(0)
	buffer_inv sc1
	s_and_saveexec_b64 s[6:7], vcc
	s_cbranch_execz .LBB0_392
	s_bcnt1_i32_b64 s0, s[4:5]
	v_mov_b32_e32 v1, s0
	v_readlane_b32 s0, v253, 43
	v_readlane_b32 s1, v253, 44
	s_nop 4
.LBB0_392:
	s_or_b64 exec, exec, s[6:7]
	s_waitcnt vmcnt(0)

; DI unsigned xb_add(unsigned* p, unsigned v) { return __hip_atomic_fetch_add(p, v, __ATOMIC_RELAXED, __HIP_MEMORY_SCOPE_AGENT); }
; DI void xcd_barrier(const XcdBarrier& b) {
;     ...
;             __builtin_amdgcn_fence(__ATOMIC_ACQUIRE, "agent");
;             xb_add(&bar[XB_XGEN(b.x)], 1u);
;             asm volatile("s_waitcnt vmcnt(0)" ::: "memory");
.LBB0_473:
	s_or_b64 exec, exec, s[4:5]
	s_mov_b64 s[4:5], exec
	v_mbcnt_lo_u32_b32 v1, s4, 0
	v_mbcnt_hi_u32_b32 v1, s5, v1
	v_cmp_eq_u32_e32 vcc, 0, v1
	s_waitcnt vmcnt(0)
	buffer_inv sc1
	s_and_saveexec_b64 s[6:7], vcc
	s_cbranch_execz .LBB0_475
	s_bcnt1_i32_b64 s0, s[4:5]
	v_mov_b32_e32 v1, s0
	v_readlane_b32 s0, v253, 43
	v_readlane_b32 s1, v253, 44
	s_nop 4
.LBB0_475:
	s_or_b64 exec, exec, s[6:7]
	s_waitcnt vmcnt(0)

; DI unsigned xb_add(unsigned* p, unsigned v) { return __hip_atomic_fetch_add(p, v, __ATOMIC_RELAXED, __HIP_MEMORY_SCOPE_AGENT); }
; DI void xcd_barrier(const XcdBarrier& b) {
;     ...
;             __builtin_amdgcn_fence(__ATOMIC_ACQUIRE, "agent");
;             xb_add(&bar[XB_XGEN(b.x)], 1u);
;             asm volatile("s_waitcnt vmcnt(0)" ::: "memory");
.LBB0_616:
	s_or_b64 exec, exec, s[4:5]
	s_mov_b64 s[4:5], exec
	v_mbcnt_lo_u32_b32 v1, s4, 0
	v_mbcnt_hi_u32_b32 v1, s5, v1
	v_cmp_eq_u32_e32 vcc, 0, v1
	s_waitcnt vmcnt(0)
	buffer_inv sc1
	s_and_saveexec_b64 s[6:7], vcc
	s_cbranch_execz .LBB0_618
	s_bcnt1_i32_b64 s0, s[4:5]
	v_mov_b32_e32 v1, s0
	v_readlane_b32 s0, v253, 43
	v_readlane_b32 s1, v253, 44
	s_nop 4
.LBB0_618:
	s_or_b64 exec, exec, s[6:7]
	s_waitcnt vmcnt(0)

; DI unsigned xb_add(unsigned* p, unsigned v) { return __hip_atomic_fetch_add(p, v, __ATOMIC_RELAXED, __HIP_MEMORY_SCOPE_AGENT); }
; DI void xcd_barrier(const XcdBarrier& b) {
;     ...
;             __builtin_amdgcn_fence(__ATOMIC_ACQUIRE, "agent");
;             xb_add(&bar[XB_XGEN(b.x)], 1u);
;             asm volatile("s_waitcnt vmcnt(0)" ::: "memory");
.LBB0_734:
	s_or_b64 exec, exec, s[6:7]
	s_mov_b64 s[6:7], exec
	v_mbcnt_lo_u32_b32 v1, s6, 0
	v_mbcnt_hi_u32_b32 v1, s7, v1
	v_cmp_eq_u32_e32 vcc, 0, v1
	s_waitcnt vmcnt(0)
	buffer_inv sc1
	s_and_saveexec_b64 s[8:9], vcc
	s_cbranch_execz .LBB0_736
	s_bcnt1_i32_b64 s0, s[6:7]
	v_mov_b32_e32 v1, s0
	v_readlane_b32 s0, v253, 43
	v_readlane_b32 s1, v253, 44
	s_nop 4
.LBB0_736:
	s_or_b64 exec, exec, s[8:9]
	s_waitcnt vmcnt(0)

; DI unsigned xb_add(unsigned* p, unsigned v) { return __hip_atomic_fetch_add(p, v, __ATOMIC_RELAXED, __HIP_MEMORY_SCOPE_AGENT); }
; DI void xcd_barrier(const XcdBarrier& b) {
;     ...
;             __builtin_amdgcn_fence(__ATOMIC_ACQUIRE, "agent");
;             xb_add(&bar[XB_XGEN(b.x)], 1u);
;             asm volatile("s_waitcnt vmcnt(0)" ::: "memory");
.LBB0_874:
	s_or_b64 exec, exec, s[4:5]
	s_mov_b64 s[4:5], exec
	v_mbcnt_lo_u32_b32 v1, s4, 0
	v_mbcnt_hi_u32_b32 v1, s5, v1
	v_cmp_eq_u32_e32 vcc, 0, v1
	s_waitcnt vmcnt(0)
	buffer_inv sc1
	s_and_saveexec_b64 s[6:7], vcc
	s_cbranch_execz .LBB0_72
	s_bcnt1_i32_b64 s0, s[4:5]
	v_mov_b32_e32 v1, s0
	v_readlane_b32 s0, v253, 43
	v_readlane_b32 s1, v253, 44
	s_nop 4
	s_branch .LBB0_72
